# attention unit prologue: first K tile requested together with the Q / own-K / k-norm loads
# speedup vs baseline: 1.2586x; 1.2586x over previous
; __device__ __forceinline__ void attn_unit_pp(int b, int h, int qb, int par, const bf16_t* __restrict__ QBp, const bf16_t* __restrict__ KBp, const bf16_t* __restrict__ VBp, ...
;     ...
;   for (int d0 = 0; d0 < 4; ++d0) { const u32x4 w = __builtin_bit_cast(u32x4, qr[d0]);
; #pragma unroll
;     for (int e = 0; e < 4; ++e) { const float lo = __uint_as_float(w[e] << 16), hh = __uint_as_float(w[e] & 0xffff0000u); qn = fmaf(lo, lo, qn); qn = fmaf(hh, hh, qn); } }
;   { auto rr = __builtin_amdgcn_permlane32_swap(__float_as_uint(qn), __float_as_uint(qn), false, false); qn = __uint_as_float(rr[0]) + __uint_as_float(rr[1]); }
;   float sii = 0.f;
;   { const bf16_t* Kw = Kh + (size_t)(q0 + w4 * QBLK + r32) * LD + g * 64 + hi * 8;
; #pragma unroll
;     for (int d0 = 0; d0 < 4; ++d0) { const u32x4 wq = __builtin_bit_cast(u32x4, qr[d0]); const u32x4 wk = __builtin_bit_cast(u32x4, ld8(Kw + d0 * 16));
; #pragma unroll
;       for (int e = 0; e < 4; ++e) { sii = fmaf(__uint_as_float(wq[e] << 16), __uint_as_float(wk[e] << 16), sii); sii = fmaf(__uint_as_float(wq[e] & 0xffff0000u), __uint_as_float(wk[e] & 0xffff0000u), sii); } } }
;   { auto rr = __builtin_amdgcn_permlane32_swap(__float_as_uint(sii), __float_as_uint(sii), false, false); sii = __uint_as_float(rr[0]) + __uint_as_float(rr[1]); }
;   { const unsigned* nk = nrmk + ((size_t)((b * 8 + h) * 2 + g)) * 2; const float kn = __uint_as_float(__hip_atomic_load(nk, __ATOMIC_RELAXED, __HIP_MEMORY_SCOPE_AGENT)) + __uint_as_float(__hip_atomic_load(nk + 1, __ATOMIC_RELAXED, __HIP_MEMORY_SCOPE_AGENT));
;     qn = sqrtf(qn * kn) * 1.02f - sii; }
;     ...
;   for (int i = 0; i < 4; ++i) stg[i] = ld8(Kh + (long)(TILE(g) * KVBLK + sr + 16 * i) * LD + sc);
.LBB0_350:
	s_lshl_b64 s[0:1], s[16:17], 18
	s_lshl_b64 s[14:15], s[0:1], 1
	v_lshlrev_b32_e32 v8, 7, v5
	s_add_u32 s2, s42, s14
	s_addc_u32 s3, s43, s15
	v_lshlrev_b32_e32 v8, 1, v8
	v_mov_b32_e32 v9, v1
	v_lshlrev_b32_e32 v10, 3, v6
	v_lshl_add_u64 v[8:9], s[2:3], 0, v[8:9]
	v_lshl_add_u64 v[8:9], s[46:47], 1, v[8:9]
	v_lshlrev_b32_e32 v168, 1, v10
	v_mov_b32_e32 v169, v1
	v_lshl_add_u64 v[24:25], v[8:9], 0, v[168:169]
	global_load_dwordx4 v[8:11], v[24:25], off
	global_load_dwordx4 v[12:15], v[24:25], off offset:32
	global_load_dwordx4 v[20:23], v[24:25], off offset:64
	s_lshl_b32 s0, s16, 1
	global_load_dwordx4 v[24:27], v[24:25], off offset:96
	s_add_i32 s0, s38, s0
	s_ashr_i32 s1, s0, 31
	s_lshl_b64 s[0:1], s[0:1], 3
	s_add_u32 s0, s30, s0
	s_addc_u32 s1, s31, s1
	global_load_dword v57, v1, s[0:1] sc1
	global_load_dword v58, v1, s[0:1] offset:4 sc1
	s_lshl_b32 s98, s22, 1
	s_add_i32 s98, s98, s38
	v_lshl_or_b32 v204, s98, 6, v7
	v_lshlrev_b32_e32 v204, 8, v204
	v_add_u32_e32 v204, v204, v2
	global_load_dwordx4 v[146:149], v204, s[2:3]
	v_add_u32_e32 v208, 0x1000, v204
	global_load_dwordx4 v[150:153], v208, s[2:3]
	v_add_u32_e32 v209, 0x2000, v204
	global_load_dwordx4 v[154:157], v209, s[2:3]
	v_add_u32_e32 v210, 0x3000, v204
	global_load_dwordx4 v[158:161], v210, s[2:3]
	s_waitcnt vmcnt(13)
	v_lshlrev_b32_e32 v28, 16, v130
	v_and_b32_e32 v29, 0xffff0000, v130
	v_fma_f32 v30, v28, v28, 0
	v_fmac_f32_e32 v30, v29, v29
	v_lshlrev_b32_e32 v31, 16, v131
	v_and_b32_e32 v32, 0xffff0000, v131
	v_fmac_f32_e32 v30, v31, v31
	v_fmac_f32_e32 v30, v32, v32
	v_lshlrev_b32_e32 v33, 16, v132
	v_and_b32_e32 v34, 0xffff0000, v132
	v_fmac_f32_e32 v30, v33, v33
	v_fmac_f32_e32 v30, v34, v34
	v_lshlrev_b32_e32 v35, 16, v133
	v_and_b32_e32 v36, 0xffff0000, v133
	v_fmac_f32_e32 v30, v35, v35
	v_fmac_f32_e32 v30, v36, v36
	s_waitcnt vmcnt(12)
	v_lshlrev_b32_e32 v37, 16, v134
	v_and_b32_e32 v38, 0xffff0000, v134
	v_fmac_f32_e32 v30, v37, v37
	v_fmac_f32_e32 v30, v38, v38
	v_lshlrev_b32_e32 v39, 16, v135
	v_and_b32_e32 v40, 0xffff0000, v135
	v_fmac_f32_e32 v30, v39, v39
	v_fmac_f32_e32 v30, v40, v40
	v_lshlrev_b32_e32 v41, 16, v136
	v_and_b32_e32 v42, 0xffff0000, v136
	v_fmac_f32_e32 v30, v41, v41
	v_fmac_f32_e32 v30, v42, v42
	v_lshlrev_b32_e32 v43, 16, v137
	v_and_b32_e32 v44, 0xffff0000, v137
	v_fmac_f32_e32 v30, v43, v43
	v_fmac_f32_e32 v30, v44, v44
	s_waitcnt vmcnt(11)
	v_lshlrev_b32_e32 v45, 16, v138
	v_and_b32_e32 v46, 0xffff0000, v138
	v_fmac_f32_e32 v30, v45, v45
	v_fmac_f32_e32 v30, v46, v46
	v_lshlrev_b32_e32 v47, 16, v139
	v_and_b32_e32 v48, 0xffff0000, v139
	v_fmac_f32_e32 v30, v47, v47
	v_fmac_f32_e32 v30, v48, v48
	v_lshlrev_b32_e32 v49, 16, v140
	v_and_b32_e32 v50, 0xffff0000, v140
	v_fmac_f32_e32 v30, v49, v49
	v_fmac_f32_e32 v30, v50, v50
	v_lshlrev_b32_e32 v51, 16, v141
	v_and_b32_e32 v52, 0xffff0000, v141
	v_fmac_f32_e32 v30, v51, v51
	v_fmac_f32_e32 v30, v52, v52
	s_waitcnt vmcnt(10)
	v_lshlrev_b32_e32 v53, 16, v142
	v_and_b32_e32 v54, 0xffff0000, v142
	v_fmac_f32_e32 v30, v53, v53
	v_fmac_f32_e32 v30, v54, v54
	v_lshlrev_b32_e32 v55, 16, v143
	v_and_b32_e32 v56, 0xffff0000, v143
	v_fmac_f32_e32 v30, v55, v55
	v_fmac_f32_e32 v30, v56, v56
	v_lshlrev_b32_e32 v59, 16, v144
	v_and_b32_e32 v60, 0xffff0000, v144
	v_fmac_f32_e32 v30, v59, v59
	v_fmac_f32_e32 v30, v60, v60
	v_lshlrev_b32_e32 v61, 16, v145
	v_and_b32_e32 v62, 0xffff0000, v145
	v_fmac_f32_e32 v30, v61, v61
	v_fmac_f32_e32 v30, v62, v62
	v_mov_b32_e32 v63, v30
	s_nop 1
	v_permlane32_swap_b32_e32 v30, v63
	v_and_b32_e32 v186, 63, v4
	v_lshlrev_b32_e32 v187, 2, v186
	s_waitcnt vmcnt(9)
; __device__ __forceinline__ void attn_unit_pp(int b, int h, int qb, int par, const bf16_t* __restrict__ QBp, const bf16_t* __restrict__ KBp, const bf16_t* __restrict__ VBp, ...
;     ...
;   float sii = 0.f;
;   { const bf16_t* Kw = Kh + (size_t)(q0 + w4 * QBLK + r32) * LD + g * 64 + hi * 8;
; #pragma unroll
;     for (int d0 = 0; d0 < 4; ++d0) { const u32x4 wq = __builtin_bit_cast(u32x4, qr[d0]); const u32x4 wk = __builtin_bit_cast(u32x4, ld8(Kw + d0 * 16));
; #pragma unroll
;       for (int e = 0; e < 4; ++e) { sii = fmaf(__uint_as_float(wq[e] << 16), __uint_as_float(wk[e] << 16), sii); sii = fmaf(__uint_as_float(wq[e] & 0xffff0000u), __uint_as_float(wk[e] & 0xffff0000u), sii); } } }
;   { auto rr = __builtin_amdgcn_permlane32_swap(__float_as_uint(sii), __float_as_uint(sii), false, false); sii = __uint_as_float(rr[0]) + __uint_as_float(rr[1]); }
;   { const unsigned* nk = nrmk + ((size_t)((b * 8 + h) * 2 + g)) * 2; const float kn = __uint_as_float(__hip_atomic_load(nk, __ATOMIC_RELAXED, __HIP_MEMORY_SCOPE_AGENT)) + __uint_as_float(__hip_atomic_load(nk + 1, __ATOMIC_RELAXED, __HIP_MEMORY_SCOPE_AGENT));
;     qn = sqrtf(qn * kn) * 1.02f - sii; }
; #pragma unroll
;   for (int x = 1; x < 32; x <<= 1) qn = fmaxf(qn, __builtin_bit_cast(float, __builtin_amdgcn_ds_bpermute((lane ^ x) << 2, __builtin_bit_cast(int, qn))));
;   float* xb = (float*)(lds + 143360 + 128) + par * 16;
;   if (lane == 0) xb[wid] = qn;
	v_lshlrev_b32_e32 v64, 16, v8
	v_fma_f32 v28, v28, v64, 0
	v_and_b32_e32 v8, 0xffff0000, v8
	v_fmac_f32_e32 v28, v29, v8
	v_lshlrev_b32_e32 v8, 16, v9
	v_fmac_f32_e32 v28, v31, v8
	v_and_b32_e32 v8, 0xffff0000, v9
	v_fmac_f32_e32 v28, v32, v8
	v_lshlrev_b32_e32 v8, 16, v10
	v_fmac_f32_e32 v28, v33, v8
	v_and_b32_e32 v8, 0xffff0000, v10
	v_fmac_f32_e32 v28, v34, v8
	v_lshlrev_b32_e32 v8, 16, v11
	v_fmac_f32_e32 v28, v35, v8
	v_and_b32_e32 v8, 0xffff0000, v11
	v_fmac_f32_e32 v28, v36, v8
	s_waitcnt vmcnt(8)
	v_lshlrev_b32_e32 v8, 16, v12
	v_fmac_f32_e32 v28, v37, v8
	v_and_b32_e32 v8, 0xffff0000, v12
	v_fmac_f32_e32 v28, v38, v8
	v_lshlrev_b32_e32 v8, 16, v13
	v_fmac_f32_e32 v28, v39, v8
	v_and_b32_e32 v8, 0xffff0000, v13
	v_fmac_f32_e32 v28, v40, v8
	v_lshlrev_b32_e32 v8, 16, v14
	v_fmac_f32_e32 v28, v41, v8
	v_and_b32_e32 v8, 0xffff0000, v14
	v_fmac_f32_e32 v28, v42, v8
	v_lshlrev_b32_e32 v8, 16, v15
	v_fmac_f32_e32 v28, v43, v8
	v_and_b32_e32 v8, 0xffff0000, v15
	v_fmac_f32_e32 v28, v44, v8
	s_waitcnt vmcnt(7)
	v_lshlrev_b32_e32 v8, 16, v20
	v_fmac_f32_e32 v28, v45, v8
	v_and_b32_e32 v8, 0xffff0000, v20
	v_fmac_f32_e32 v28, v46, v8
	v_lshlrev_b32_e32 v8, 16, v21
	v_fmac_f32_e32 v28, v47, v8
	v_and_b32_e32 v8, 0xffff0000, v21
	v_fmac_f32_e32 v28, v48, v8
	v_lshlrev_b32_e32 v8, 16, v22
	v_fmac_f32_e32 v28, v49, v8
	v_and_b32_e32 v8, 0xffff0000, v22
	v_fmac_f32_e32 v28, v50, v8
	v_lshlrev_b32_e32 v8, 16, v23
	v_fmac_f32_e32 v28, v51, v8
	v_and_b32_e32 v8, 0xffff0000, v23
	v_fmac_f32_e32 v28, v52, v8
	s_waitcnt vmcnt(6)
	v_lshlrev_b32_e32 v8, 16, v24
	v_fmac_f32_e32 v28, v53, v8
	v_and_b32_e32 v8, 0xffff0000, v24
	v_fmac_f32_e32 v28, v54, v8
	v_lshlrev_b32_e32 v8, 16, v25
	v_fmac_f32_e32 v28, v55, v8
	v_and_b32_e32 v8, 0xffff0000, v25
	v_fmac_f32_e32 v28, v56, v8
	v_lshlrev_b32_e32 v8, 16, v26
	v_fmac_f32_e32 v28, v59, v8
	v_and_b32_e32 v8, 0xffff0000, v26
	v_fmac_f32_e32 v28, v60, v8
	v_lshlrev_b32_e32 v8, 16, v27
	v_fmac_f32_e32 v28, v61, v8
	v_and_b32_e32 v8, 0xffff0000, v27
	v_fmac_f32_e32 v28, v62, v8
	v_add_f32_e32 v8, v30, v63
	s_waitcnt vmcnt(4)
	v_add_f32_e32 v10, v57, v58
	v_mul_f32_e32 v8, v8, v10
	v_mul_f32_e32 v10, 0x4f800000, v8
	v_cmp_gt_f32_e32 vcc, s49, v8
	v_mov_b32_e32 v9, v28
	s_nop 1
	v_permlane32_swap_b32_e32 v28, v9
	v_cndmask_b32_e32 v8, v8, v10, vcc
	v_sqrt_f32_e32 v10, v8
	v_add_f32_e32 v9, v28, v9
	v_xor_b32_e32 v183, 4, v187
	v_xor_b32_e32 v182, 8, v187
	v_add_u32_e32 v11, -1, v10
	v_fma_f32 v12, -v11, v10, v8
	v_cmp_ge_f32_e64 s[0:1], 0, v12
	v_add_u32_e32 v12, 1, v10
	v_xor_b32_e32 v181, 16, v187
	v_cndmask_b32_e64 v11, v10, v11, s[0:1]
	v_fma_f32 v10, -v12, v10, v8
	v_cmp_lt_f32_e64 s[0:1], 0, v10
	v_xor_b32_e32 v180, 32, v187
	v_xor_b32_e32 v169, 64, v187
	v_cndmask_b32_e64 v10, v11, v12, s[0:1]
	v_mul_f32_e32 v11, 0x37800000, v10
	v_cndmask_b32_e32 v10, v10, v11, vcc
	v_cmp_class_f32_e32 vcc, v8, v176
	s_lshl_b32 s0, s82, 6
	s_and_b32 s0, s0, 64
	v_cndmask_b32_e32 v8, v10, v8, vcc
	v_fma_f32 v8, v8, s50, -v9
	ds_bpermute_b32 v9, v183, v8
	s_add_i32 s11, s0, 0
	s_add_i32 s11, s11, 0x23080
	v_cmp_eq_u32_e32 vcc, 0, v186
	s_waitcnt lgkmcnt(0)
	v_max_f32_e32 v9, v9, v9
	v_max_f32_e32 v8, v8, v9
	ds_bpermute_b32 v9, v182, v8
	s_waitcnt lgkmcnt(0)
	v_max_f32_e32 v9, v9, v9
	v_max_f32_e32 v8, v8, v9
	ds_bpermute_b32 v9, v181, v8
	s_waitcnt lgkmcnt(0)
	v_max_f32_e32 v9, v9, v9
	v_max_f32_e32 v8, v8, v9
	ds_bpermute_b32 v9, v180, v8
	s_waitcnt lgkmcnt(0)
	v_max_f32_e32 v9, v9, v9
	v_max_f32_e32 v8, v8, v9
	ds_bpermute_b32 v9, v169, v8
	s_and_saveexec_b64 s[0:1], vcc
	s_cbranch_execz .LBB0_352
	s_waitcnt lgkmcnt(0)
	v_max_f32_e32 v9, v9, v9
	v_max_f32_e32 v8, v8, v8
	v_lshl_add_u32 v3, v3, 2, s11
	v_max_f32_e32 v8, v8, v9
	ds_write_b32 v3, v8

; __device__ __forceinline__ void attn_unit_pp(int b, int h, int qb, int par, const bf16_t* __restrict__ QBp, const bf16_t* __restrict__ KBp, const bf16_t* __restrict__ VBp, ...
;     ...
;   const int dt = 2 * qb, nR = jlo + n - dt;
;     ...
;   float m_run = -1e30f; int live = 0;
; #pragma unroll
;   for (int i = 0; i < 4; ++i) stg[i] = ld8(Kh + (long)(TILE(g) * KVBLK + sr + 16 * i) * LD + sc);
; #pragma unroll
;   for (int i = 0; i < 4; ++i) *(bf16x8*)(K_lds + g * SHM_K + KSWZ(sr + 16 * i, sc * 2)) = stg[i];
;   if (!g || n > 2) {
; #pragma unroll
;     for (int i = 0; i < 4; ++i) stg[i] = ld8(Tsrc + (long)(TILE(g ? 2 : 0) * KVBLK + 16 * i) * LD); }
.LBB0_358:
	s_add_u32 s11, s44, s14
	s_addc_u32 s14, s45, s15
	s_and_b64 s[0:1], exec, s[12:13]
	s_cselect_b32 s1, s14, s3
	s_cselect_b32 s0, s11, s2
	s_lshl_b32 s22, s22, 1
	s_sub_i32 s11, s16, s17
	s_sub_i32 s16, s17, s22
	s_add_i32 s23, s16, s11
	s_add_i32 s23, s23, 1
	s_not_b32 s33, s38
	s_add_i32 s39, s23, s22
	s_xor_b64 s[14:15], s[12:13], -1
	s_add_i32 s16, s38, s22
	s_add_i32 s39, s39, s33
	s_cmp_lt_i32 s38, s23
	s_cselect_b32 s16, s16, s39
	v_mov_b32_e32 v3, v1
	v_lshlrev_b32_e32 v8, 8, v7
	v_mov_b32_e32 v9, v1
	v_lshl_add_u64 v[10:11], s[0:1], 0, v[8:9]
	s_lshl_b32 s0, s38, 14
	s_add_i32 s0, s0, 0
	v_bitop3_b32 v12, v2, v4, s41 bitop3:0x78
	s_cmp_lt_i32 s11, 2
	v_lshl_add_u64 v[170:171], v[10:11], 0, v[2:3]
	v_add3_u32 v2, s0, v8, v12
	s_cselect_b64 s[0:1], -1, 0
	s_and_b64 s[0:1], s[14:15], s[0:1]
	s_and_b64 vcc, exec, s[0:1]
	s_waitcnt vmcnt(3)
	ds_write_b128 v2, v[146:149] offset:32768
	s_waitcnt vmcnt(2)
	ds_write_b128 v2, v[150:153] offset:36864
	s_waitcnt vmcnt(1)
	ds_write_b128 v2, v[154:157] offset:40960
	s_waitcnt vmcnt(0)
	ds_write_b128 v2, v[158:161] offset:45056
	s_cbranch_vccnz .LBB0_360
	s_and_b64 s[0:1], exec, s[12:13]
	s_cselect_b32 s0, 0, -2
	s_cselect_b32 s1, 0, 2
	s_add_i32 s0, s22, s0
	s_add_i32 s0, s0, s23
	s_add_i32 s2, s1, s22
	s_add_i32 s0, s0, -1
	s_cmp_lt_i32 s1, s23
	s_cselect_b32 s0, s2, s0
	s_lshl_b32 s0, s0, 6
	s_ashr_i32 s1, s0, 31
	s_lshl_b64 s[2:3], s[0:1], 8
	v_lshl_add_u64 v[2:3], v[170:171], 0, s[2:3]
	s_or_b32 s2, s0, 16
	s_ashr_i32 s3, s2, 31
	s_lshl_b64 s[2:3], s[2:3], 8
	v_lshl_add_u64 v[8:9], v[170:171], 0, s[2:3]
	s_or_b32 s2, s0, 32
	s_ashr_i32 s3, s2, 31
	s_or_b32 s0, s0, 48
	s_lshl_b64 s[2:3], s[2:3], 8
	s_ashr_i32 s1, s0, 31
	global_load_dwordx4 v[146:149], v[2:3], off
	global_load_dwordx4 v[150:153], v[8:9], off
	v_lshl_add_u64 v[2:3], v[170:171], 0, s[2:3]
	s_lshl_b64 s[0:1], s[0:1], 8
	v_lshl_add_u64 v[8:9], v[170:171], 0, s[0:1]
	global_load_dwordx4 v[154:157], v[2:3], off
	global_load_dwordx4 v[158:161], v[8:9], off
